# attention VALU diet + first exps of each PV phase placed after that gap's ds_reads (keeps 12 wait states behind the last QK MFMA)
# speedup vs baseline: 1.0028x; 1.0028x over previous
.LBB0_304:
	s_mov_b32 s37, s28
	s_mov_b32 s14, s27
	v_lshl_add_u32 v65, s15, 1, v239
	ds_read_b64_tr_b16 v[72:73], v65 offset:24576
	ds_read_b64_tr_b16 v[74:75], v65 offset:25088
	v_add_f32_e32 v68, v96, v97
	v_add_f32_e32 v68, v98, v68
	v_add_f32_e32 v68, v99, v68
	v_add_f32_e32 v68, v100, v68
	v_add_f32_e32 v68, v101, v68
	v_cvt_pk_bf16_f32 v172, v96, v97
	v_cvt_pk_bf16_f32 v173, v98, v99
	s_waitcnt lgkmcnt(9)
	v_mfma_f32_32x32x16_bf16 v[128:143], v[204:207], v[168:171], 0
	ds_read_b64_tr_b16 v[76:77], v65 offset:28672
	ds_read_b64_tr_b16 v[78:79], v65 offset:29184
	v_add_f32_e32 v68, v102, v68
	v_add_f32_e32 v68, v103, v68
	v_add_f32_e32 v68, v104, v68
	v_add_f32_e32 v68, v105, v68
	v_cvt_pk_bf16_f32 v174, v100, v101
	v_cvt_pk_bf16_f32 v175, v102, v103
	s_waitcnt lgkmcnt(10)
	v_mfma_f32_32x32x16_bf16 v[112:127], v[200:203], v[168:171], 0
	ds_read_b64_tr_b16 v[96:97], v65 offset:32768
	ds_read_b64_tr_b16 v[98:99], v65 offset:33280
	v_add_f32_e32 v68, v106, v68
	v_add_f32_e32 v68, v107, v68
	v_add_f32_e32 v68, v108, v68
	v_add_f32_e32 v68, v109, v68
	v_cvt_pk_bf16_f32 v164, v104, v105
	v_cvt_pk_bf16_f32 v165, v106, v107
	s_waitcnt lgkmcnt(11)
	v_mfma_f32_32x32x16_bf16 v[128:143], v[196:199], v[160:163], v[128:143]
	ds_read_b64_tr_b16 v[100:101], v65 offset:36864
	ds_read_b64_tr_b16 v[102:103], v65 offset:37376
	v_add_f32_e32 v68, v110, v68
	v_add_f32_e32 v68, v111, v68
	v_add_f32_e32 v68, v80, v68
	v_add_f32_e32 v68, v81, v68
	v_cvt_pk_bf16_f32 v166, v108, v109
	v_cvt_pk_bf16_f32 v167, v110, v111
	s_waitcnt lgkmcnt(12)
	v_mfma_f32_32x32x16_bf16 v[112:127], v[192:195], v[160:163], v[112:127]
	ds_read_b64_tr_b16 v[104:105], v65 offset:25600
	ds_read_b64_tr_b16 v[106:107], v65 offset:26112
	v_add_f32_e32 v68, v82, v68
	v_add_f32_e32 v68, v83, v68
	v_add_f32_e32 v68, v84, v68
	v_add_f32_e32 v68, v85, v68
	v_cvt_pk_bf16_f32 v156, v80, v81
	v_cvt_pk_bf16_f32 v157, v82, v83
	s_waitcnt lgkmcnt(13)
	v_mfma_f32_32x32x16_bf16 v[128:143], v[188:191], v[152:155], v[128:143]
	ds_read_b64_tr_b16 v[80:81], v65 offset:29696
	ds_read_b64_tr_b16 v[82:83], v65 offset:30208
	v_add_f32_e32 v68, v86, v68
	v_add_f32_e32 v68, v87, v68
	v_add_f32_e32 v68, v88, v68
	v_add_f32_e32 v68, v89, v68
	v_cvt_pk_bf16_f32 v158, v84, v85
	v_cvt_pk_bf16_f32 v159, v86, v87
	s_waitcnt lgkmcnt(14)
	v_mfma_f32_32x32x16_bf16 v[112:127], v[184:187], v[152:155], v[112:127]
	ds_read_b64_tr_b16 v[84:85], v65 offset:33792
	ds_read_b64_tr_b16 v[86:87], v65 offset:34304
	v_add_f32_e32 v68, v90, v68
	v_add_f32_e32 v68, v91, v68
	v_add_f32_e32 v68, v92, v68
	v_add_f32_e32 v68, v93, v68
	v_cvt_pk_bf16_f32 v148, v88, v89
	v_cvt_pk_bf16_f32 v149, v90, v91
	s_waitcnt lgkmcnt(14)
	v_mfma_f32_32x32x16_bf16 v[128:143], v[180:183], v[144:147], v[128:143]
	ds_read_b64_tr_b16 v[88:89], v65 offset:37888
	ds_read_b64_tr_b16 v[90:91], v65 offset:38400
	v_add_f32_e32 v68, v94, v68
	v_add_f32_e32 v68, v95, v68
	v_cvt_pk_bf16_f32 v150, v92, v93
	v_cvt_pk_bf16_f32 v151, v94, v95
	v_mfma_f32_32x32x16_bf16 v[112:127], v[176:179], v[144:147], v[112:127]
	v_add_f32_e32 v64, v64, v68
	s_waitcnt lgkmcnt(14)
	v_mfma_f32_32x32x16_bf16 v[48:63], v[172:175], v[72:75], v[48:63]
	ds_read_b64_tr_b16 v[72:73], v65 offset:26624
	ds_read_b64_tr_b16 v[74:75], v65 offset:27136
	v_exp_f32_e32 v128, v128
	v_exp_f32_e32 v129, v129
	s_waitcnt lgkmcnt(14)
	v_mfma_f32_32x32x16_bf16 v[32:47], v[172:175], v[76:79], v[32:47]
	v_exp_f32_e32 v130, v130
	v_exp_f32_e32 v131, v131
	ds_read_b64_tr_b16 v[76:77], v65 offset:30720
	ds_read_b64_tr_b16 v[78:79], v65 offset:31232
	s_add_i32 s15, s27, s20
	s_mov_b32 m0, s15
	s_nop 0
	global_load_lds_dwordx4 v250, s[98:99]
	s_add_u32 s98, s98, 0x60000
	s_addc_u32 s99, s99, 0
	s_waitcnt lgkmcnt(14)
	v_mfma_f32_32x32x16_bf16 v[16:31], v[172:175], v[96:99], v[16:31]
	v_exp_f32_e32 v132, v132
	v_exp_f32_e32 v133, v133
	ds_read_b64_tr_b16 v[92:93], v65 offset:34816
	ds_read_b64_tr_b16 v[94:95], v65 offset:35328
	s_waitcnt lgkmcnt(14)
	v_mfma_f32_32x32x16_bf16 v[0:15], v[172:175], v[100:103], v[0:15]
	v_exp_f32_e32 v134, v134
	v_exp_f32_e32 v135, v135
	ds_read_b64_tr_b16 v[96:97], v65 offset:38912
	ds_read_b64_tr_b16 v[98:99], v65 offset:39424
	s_waitcnt lgkmcnt(14)
	v_mfma_f32_32x32x16_bf16 v[48:63], v[164:167], v[104:107], v[48:63]
	v_exp_f32_e32 v136, v136
	v_exp_f32_e32 v137, v137
	ds_read_b64_tr_b16 v[100:101], v65 offset:27648
	ds_read_b64_tr_b16 v[102:103], v65 offset:28160
	s_lshl_b32 s15, s28, 1
	s_add_i32 s15, s15, s21
	s_mov_b32 m0, s15
	s_nop 0
	global_load_lds_dwordx4 v251, s[100:101]
	s_waitcnt lgkmcnt(14)
	v_mfma_f32_32x32x16_bf16 v[32:47], v[164:167], v[80:83], v[32:47]
	v_exp_f32_e32 v138, v138
	v_exp_f32_e32 v139, v139
	ds_read_b64_tr_b16 v[80:81], v65 offset:31744
	ds_read_b64_tr_b16 v[82:83], v65 offset:32256
	s_waitcnt lgkmcnt(14)
	v_mfma_f32_32x32x16_bf16 v[16:31], v[164:167], v[84:87], v[16:31]
	v_exp_f32_e32 v140, v140
	v_exp_f32_e32 v141, v141
	ds_read_b64_tr_b16 v[84:85], v65 offset:35840
	ds_read_b64_tr_b16 v[86:87], v65 offset:36352
	s_waitcnt lgkmcnt(14)
	v_mfma_f32_32x32x16_bf16 v[0:15], v[164:167], v[88:91], v[0:15]
	v_exp_f32_e32 v142, v142
	v_exp_f32_e32 v143, v143
	ds_read_b64_tr_b16 v[88:89], v65 offset:39936
	ds_read_b64_tr_b16 v[90:91], v65 offset:40448
	s_lshl_b32 s15, s28, 1
	s_add_i32 s15, s15, s21
	s_addk_i32 s15, 0x1f80
	s_mov_b32 m0, s15
	s_nop 0
	global_load_lds_dwordx4 v251, s[100:101] offset:128
	s_add_u32 s100, s100, 0x60000
	s_addc_u32 s101, s101, 0
	s_waitcnt lgkmcnt(14)
	v_mfma_f32_32x32x16_bf16 v[48:63], v[156:159], v[72:75], v[48:63]
	v_exp_f32_e32 v112, v112
	v_exp_f32_e32 v113, v113
	s_waitcnt lgkmcnt(12)
	v_mfma_f32_32x32x16_bf16 v[32:47], v[156:159], v[76:79], v[32:47]
	v_exp_f32_e32 v114, v114
	v_exp_f32_e32 v115, v115
	v_add_u32_e32 v65, s37, v241
	ds_read_b128 v[72:75], v65
	ds_read_b128 v[76:79], v65 offset:512
	s_waitcnt lgkmcnt(12)
	v_mfma_f32_32x32x16_bf16 v[16:31], v[156:159], v[92:95], v[16:31]
	v_exp_f32_e32 v116, v116
	v_exp_f32_e32 v117, v117
	ds_read_b128 v[176:179], v65 offset:2048
	ds_read_b128 v[180:183], v65 offset:2560
	s_waitcnt lgkmcnt(12)
	v_mfma_f32_32x32x16_bf16 v[0:15], v[156:159], v[96:99], v[0:15]
	v_exp_f32_e32 v118, v118
	v_exp_f32_e32 v119, v119
	ds_read_b128 v[184:187], v65 offset:4096
	ds_read_b128 v[188:191], v65 offset:4608
	s_waitcnt lgkmcnt(12)
	v_mfma_f32_32x32x16_bf16 v[48:63], v[148:151], v[100:103], v[48:63]
	v_exp_f32_e32 v120, v120
	v_exp_f32_e32 v121, v121
	ds_read_b128 v[192:195], v65 offset:6144
	ds_read_b128 v[196:199], v65 offset:6656
	s_waitcnt lgkmcnt(12)
	v_mfma_f32_32x32x16_bf16 v[32:47], v[148:151], v[80:83], v[32:47]
	v_exp_f32_e32 v122, v122
	v_exp_f32_e32 v123, v123
	s_waitcnt lgkmcnt(10)
	v_mfma_f32_32x32x16_bf16 v[16:31], v[148:151], v[84:87], v[16:31]
	v_exp_f32_e32 v124, v124
	v_exp_f32_e32 v125, v125
	s_waitcnt lgkmcnt(8)
	v_mfma_f32_32x32x16_bf16 v[0:15], v[148:151], v[88:91], v[0:15]
	v_exp_f32_e32 v126, v126
	v_exp_f32_e32 v127, v127
	s_waitcnt vmcnt(3) lgkmcnt(0)
	s_barrier
	s_add_i32 s15, s28, 0x2000
	s_cmpk_lg_i32 s28, 0x4000
	s_cselect_b32 s27, s15, 0
	v_lshl_add_u32 v65, s14, 1, v239
	ds_read_b64_tr_b16 v[200:201], v65 offset:24576
	ds_read_b64_tr_b16 v[202:203], v65 offset:25088
	s_waitcnt lgkmcnt(9)
	v_mfma_f32_32x32x16_bf16 v[96:111], v[72:75], v[168:171], 0
	v_add_f32_e32 v80, v128, v129
	v_add_f32_e32 v80, v130, v80
	v_add_f32_e32 v80, v131, v80
	v_add_f32_e32 v80, v132, v80
	v_add_f32_e32 v80, v133, v80
	v_cvt_pk_bf16_f32 v172, v128, v129
	v_cvt_pk_bf16_f32 v173, v130, v131
	ds_read_b64_tr_b16 v[72:73], v65 offset:28672
	ds_read_b64_tr_b16 v[74:75], v65 offset:29184
	v_add_f32_e32 v80, v134, v80
	v_add_f32_e32 v80, v135, v80
	v_add_f32_e32 v80, v136, v80
	v_add_f32_e32 v128, v137, v80
	s_waitcnt lgkmcnt(10)
	v_mfma_f32_32x32x16_bf16 v[80:95], v[76:79], v[168:171], 0
	v_cvt_pk_bf16_f32 v174, v132, v133
	v_cvt_pk_bf16_f32 v175, v134, v135
	ds_read_b64_tr_b16 v[76:77], v65 offset:32768
	ds_read_b64_tr_b16 v[78:79], v65 offset:33280
	s_waitcnt lgkmcnt(11)
	v_mfma_f32_32x32x16_bf16 v[96:111], v[176:179], v[160:163], v[96:111]
	v_add_f32_e32 v128, v138, v128
	v_add_f32_e32 v128, v139, v128
	v_add_f32_e32 v128, v140, v128
	v_add_f32_e32 v132, v141, v128
	v_cvt_pk_bf16_f32 v164, v136, v137
	v_cvt_pk_bf16_f32 v165, v138, v139
	ds_read_b64_tr_b16 v[128:129], v65 offset:36864
	ds_read_b64_tr_b16 v[130:131], v65 offset:37376
	s_waitcnt lgkmcnt(12)
	v_mfma_f32_32x32x16_bf16 v[80:95], v[180:183], v[160:163], v[80:95]
	v_add_f32_e32 v132, v142, v132
	v_add_f32_e32 v132, v143, v132
	v_add_f32_e32 v132, v112, v132
	v_add_f32_e32 v136, v113, v132
	v_cvt_pk_bf16_f32 v166, v140, v141
	v_cvt_pk_bf16_f32 v167, v142, v143
	ds_read_b64_tr_b16 v[132:133], v65 offset:25600
	ds_read_b64_tr_b16 v[134:135], v65 offset:26112
	s_waitcnt lgkmcnt(13)
	v_mfma_f32_32x32x16_bf16 v[96:111], v[184:187], v[152:155], v[96:111]
	v_add_f32_e32 v136, v114, v136
	v_add_f32_e32 v136, v115, v136
	v_add_f32_e32 v136, v116, v136
	v_add_f32_e32 v136, v117, v136
	v_cvt_pk_bf16_f32 v156, v112, v113
	v_cvt_pk_bf16_f32 v157, v114, v115
	ds_read_b64_tr_b16 v[112:113], v65 offset:29696
	ds_read_b64_tr_b16 v[114:115], v65 offset:30208
	s_waitcnt lgkmcnt(14)
	v_mfma_f32_32x32x16_bf16 v[80:95], v[188:191], v[152:155], v[80:95]
	v_add_f32_e32 v136, v118, v136
	v_add_f32_e32 v136, v119, v136
	v_add_f32_e32 v136, v120, v136
	v_add_f32_e32 v136, v121, v136
	v_cvt_pk_bf16_f32 v158, v116, v117
	v_cvt_pk_bf16_f32 v159, v118, v119
	ds_read_b64_tr_b16 v[116:117], v65 offset:33792
	ds_read_b64_tr_b16 v[118:119], v65 offset:34304
	s_waitcnt lgkmcnt(14)
	v_mfma_f32_32x32x16_bf16 v[96:111], v[192:195], v[144:147], v[96:111]
	v_add_f32_e32 v136, v122, v136
	v_add_f32_e32 v136, v123, v136
	v_add_f32_e32 v136, v124, v136
	v_add_f32_e32 v136, v125, v136
	v_cvt_pk_bf16_f32 v148, v120, v121
	v_cvt_pk_bf16_f32 v149, v122, v123
	ds_read_b64_tr_b16 v[120:121], v65 offset:37888
	ds_read_b64_tr_b16 v[122:123], v65 offset:38400
	v_mfma_f32_32x32x16_bf16 v[80:95], v[196:199], v[144:147], v[80:95]
	v_add_f32_e32 v136, v126, v136
	v_add_f32_e32 v136, v127, v136
	v_cvt_pk_bf16_f32 v150, v124, v125
	v_cvt_pk_bf16_f32 v151, v126, v127
	v_add_f32_e32 v64, v64, v136
	s_add_i32 s35, s35, 2
	s_waitcnt lgkmcnt(14)
	v_mfma_f32_32x32x16_bf16 v[48:63], v[172:175], v[200:203], v[48:63]
	ds_read_b64_tr_b16 v[68:69], v65 offset:26624
	ds_read_b64_tr_b16 v[70:71], v65 offset:27136
	v_exp_f32_e32 v96, v96
	v_exp_f32_e32 v97, v97
	s_waitcnt lgkmcnt(14)
	v_mfma_f32_32x32x16_bf16 v[32:47], v[172:175], v[72:75], v[32:47]
	v_exp_f32_e32 v98, v98
	v_exp_f32_e32 v99, v99
	ds_read_b64_tr_b16 v[72:73], v65 offset:30720
	ds_read_b64_tr_b16 v[74:75], v65 offset:31232
	s_add_i32 s24, s28, s20
	s_mov_b32 m0, s24
	s_nop 0
	global_load_lds_dwordx4 v250, s[98:99]
	s_add_u32 s98, s98, 0x60000
	s_addc_u32 s99, s99, 0
	s_waitcnt lgkmcnt(14)
; #define WAIT_BAR(N) asm volatile("s_waitcnt vmcnt(" #N ") lgkmcnt(0)\n\ts_barrier":::"memory")
;   #define ROT() do{sl_prev=sl_cur;sl_cur=sl_next;sl_next=(sl_next==(NSLOT-1)*SLOTB)?0:sl_next+SLOTB;}while(0)
; template<int DUMMY> __device__ __forceinline__ void attn_pass2(const bf16*Qh,const bf16*__restrict__ Kh,const bf16*__restrict__ Vh,const int q0,char*shm,f32x16 (&o)[4]){
;     ...
;   int t=1;
;     ...
;   for(;t+5<NT;t+=2){
;     STEP(pB0,pB1,pA0,pA1,t,true,true,true);     WAIT_BAR(3); ROT();
;     STEP(pA0,pA1,pB0,pB1,t+1,true,true,true);   WAIT_BAR(3); ROT();
	v_mfma_f32_32x32x16_bf16 v[16:31], v[172:175], v[76:79], v[16:31]
	v_exp_f32_e32 v100, v100
	v_exp_f32_e32 v101, v101
	ds_read_b64_tr_b16 v[76:77], v65 offset:34816
	ds_read_b64_tr_b16 v[78:79], v65 offset:35328
	s_waitcnt lgkmcnt(14)
	v_mfma_f32_32x32x16_bf16 v[0:15], v[172:175], v[128:131], v[0:15]
	v_exp_f32_e32 v102, v102
	v_exp_f32_e32 v103, v103
	ds_read_b64_tr_b16 v[124:125], v65 offset:38912
	ds_read_b64_tr_b16 v[126:127], v65 offset:39424
	s_waitcnt lgkmcnt(14)
	v_mfma_f32_32x32x16_bf16 v[48:63], v[164:167], v[132:135], v[48:63]
	v_exp_f32_e32 v104, v104
	v_exp_f32_e32 v105, v105
	ds_read_b64_tr_b16 v[128:129], v65 offset:27648
	ds_read_b64_tr_b16 v[130:131], v65 offset:28160
	s_lshl_b32 s24, s27, 1
	s_add_i32 s24, s24, s21
	s_mov_b32 m0, s24
	s_nop 0
	global_load_lds_dwordx4 v251, s[100:101]
	s_waitcnt lgkmcnt(14)
	v_mfma_f32_32x32x16_bf16 v[32:47], v[164:167], v[112:115], v[32:47]
	v_exp_f32_e32 v106, v106
	v_exp_f32_e32 v107, v107
	ds_read_b64_tr_b16 v[112:113], v65 offset:31744
	ds_read_b64_tr_b16 v[114:115], v65 offset:32256
	s_waitcnt lgkmcnt(14)
	v_mfma_f32_32x32x16_bf16 v[16:31], v[164:167], v[116:119], v[16:31]
	v_exp_f32_e32 v108, v108
	v_exp_f32_e32 v109, v109
	ds_read_b64_tr_b16 v[116:117], v65 offset:35840
	ds_read_b64_tr_b16 v[118:119], v65 offset:36352
	s_waitcnt lgkmcnt(14)
	v_mfma_f32_32x32x16_bf16 v[0:15], v[164:167], v[120:123], v[0:15]
	v_exp_f32_e32 v110, v110
	v_exp_f32_e32 v111, v111
	ds_read_b64_tr_b16 v[120:121], v65 offset:39936
	ds_read_b64_tr_b16 v[122:123], v65 offset:40448
	s_lshl_b32 s24, s27, 1
	s_add_i32 s24, s24, s21
	s_addk_i32 s24, 0x1f80
	s_mov_b32 m0, s24
	s_nop 0
	global_load_lds_dwordx4 v251, s[100:101] offset:128
	s_add_u32 s100, s100, 0x60000
	s_addc_u32 s101, s101, 0
	s_waitcnt lgkmcnt(14)
	v_mfma_f32_32x32x16_bf16 v[48:63], v[156:159], v[68:71], v[48:63]
	v_exp_f32_e32 v80, v80
	v_exp_f32_e32 v81, v81
	s_waitcnt lgkmcnt(12)
	v_mfma_f32_32x32x16_bf16 v[32:47], v[156:159], v[72:75], v[32:47]
	v_exp_f32_e32 v82, v82
	v_exp_f32_e32 v83, v83
	v_add_u32_e32 v65, s27, v241
	ds_read_b128 v[204:207], v65
	ds_read_b128 v[200:203], v65 offset:512
	s_waitcnt lgkmcnt(12)
	v_mfma_f32_32x32x16_bf16 v[16:31], v[156:159], v[76:79], v[16:31]
	v_exp_f32_e32 v84, v84
	v_exp_f32_e32 v85, v85
	ds_read_b128 v[196:199], v65 offset:2048
	ds_read_b128 v[192:195], v65 offset:2560
	s_waitcnt lgkmcnt(12)
	v_mfma_f32_32x32x16_bf16 v[0:15], v[156:159], v[124:127], v[0:15]
	v_exp_f32_e32 v86, v86
	v_exp_f32_e32 v87, v87
	ds_read_b128 v[188:191], v65 offset:4096
	ds_read_b128 v[184:187], v65 offset:4608
	s_waitcnt lgkmcnt(12)
	v_mfma_f32_32x32x16_bf16 v[48:63], v[148:151], v[128:131], v[48:63]
	v_exp_f32_e32 v88, v88
	v_exp_f32_e32 v89, v89
	ds_read_b128 v[180:183], v65 offset:6144
	ds_read_b128 v[176:179], v65 offset:6656
	s_waitcnt lgkmcnt(12)
	v_mfma_f32_32x32x16_bf16 v[32:47], v[148:151], v[112:115], v[32:47]
	v_exp_f32_e32 v90, v90
	v_exp_f32_e32 v91, v91
	s_waitcnt lgkmcnt(10)
	v_mfma_f32_32x32x16_bf16 v[16:31], v[148:151], v[116:119], v[16:31]
	v_exp_f32_e32 v92, v92
	v_exp_f32_e32 v93, v93
	s_waitcnt lgkmcnt(8)
	v_mfma_f32_32x32x16_bf16 v[0:15], v[148:151], v[120:123], v[0:15]
	v_exp_f32_e32 v94, v94
	v_exp_f32_e32 v95, v95
	s_add_i32 s14, s27, 0x2000
	s_cmpk_lg_i32 s27, 0x4000
	s_waitcnt vmcnt(3) lgkmcnt(0)
	s_barrier
	s_cselect_b32 s28, s14, 0
	s_add_u32 s56, s56, 0xc0000
	s_addc_u32 s57, s57, 0
	s_cmp_ge_i32 s35, s11
	s_mov_b32 s15, s37
	s_cbranch_scc0 .LBB0_304
	s_ashr_i32 s11, s10, 31
	s_add_i32 s14, s35, 1
	s_cmp_lt_i32 s14, s25
	s_cbranch_scc1 .LBB0_315
